# scan pass 2: chunk-prefix steps double-buffered (next 8 steps' loads in flight while the current 8 are folded), on top of the merged attention+scan phase
# speedup vs baseline: 1.0007x; 1.0007x over previous
; DEV int ltid() { int t = threadIdx.x; asm volatile("" : "+v"(t)); return t; }
; DEV void ph_scan2(const Params& p, int item) {
;   const int b = item / NCH, c = item % NCH, ch = ltid() * 4;
;   float H[4] = {0.f, 0.f, 0.f, 0.f};
;   for (int c2 = 0; c2 < c; ++c2) {
;     float4 a = *(const float4*)(p.csA + (size_t)(b * NCH + c2) * 1024 + ch);
;     float4 hh = *(const float4*)(p.csH + (size_t)(b * NCH + c2) * 1024 + ch);
;     H[0] = a.x * H[0] + hh.x; H[1] = a.y * H[1] + hh.y; H[2] = a.z * H[2] + hh.z; H[3] = a.w * H[3] + hh.w;
;   }
.Lsc_item:
	s_lshr_b32 s48, s50, 6
	s_and_b32 s49, s50, 63
	v_mov_b32_e32 v4, 0
	v_mov_b32_e32 v5, 0
	v_mov_b32_e32 v6, 0
	v_mov_b32_e32 v7, 0
	v_readlane_b32 s24, v255, 33
	v_readlane_b32 s25, v255, 34
	v_readlane_b32 s26, v255, 35
	v_readlane_b32 s27, v255, 36
	s_lshl_b32 s38, s48, 18
	s_add_u32 s24, s24, s38
	s_addc_u32 s25, s25, 0
	s_add_u32 s26, s26, s38
	s_addc_u32 s27, s27, 0
	s_mov_b32 s45, 0
	s_and_b32 s8, s49, 7
	s_lshr_b32 s9, s49, 3
	s_cmp_eq_u32 s8, 0
	s_cbranch_scc1 .Lsc_remdone
	s_cmp_gt_u32 s8, 0
	s_cbranch_scc0 .Lsc_pl0
	global_load_dwordx4 v[10:13], v1, s[24:25]
	global_load_dwordx4 v[14:17], v1, s[26:27]
	s_add_u32 s24, s24, 0x1000
	s_addc_u32 s25, s25, 0
	s_add_u32 s26, s26, 0x1000
	s_addc_u32 s27, s27, 0
.Lsc_pl0:
	s_cmp_gt_u32 s8, 1
	s_cbranch_scc0 .Lsc_pl1
	global_load_dwordx4 v[18:21], v1, s[24:25]
	global_load_dwordx4 v[22:25], v1, s[26:27]
	s_add_u32 s24, s24, 0x1000
	s_addc_u32 s25, s25, 0
	s_add_u32 s26, s26, 0x1000
	s_addc_u32 s27, s27, 0
.Lsc_pl1:
	s_cmp_gt_u32 s8, 2
	s_cbranch_scc0 .Lsc_pl2
	global_load_dwordx4 v[26:29], v1, s[24:25]
	global_load_dwordx4 v[30:33], v1, s[26:27]
	s_add_u32 s24, s24, 0x1000
	s_addc_u32 s25, s25, 0
	s_add_u32 s26, s26, 0x1000
	s_addc_u32 s27, s27, 0
.Lsc_pl2:
	s_cmp_gt_u32 s8, 3
	s_cbranch_scc0 .Lsc_pl3
	global_load_dwordx4 v[34:37], v1, s[24:25]
	global_load_dwordx4 v[38:41], v1, s[26:27]
	s_add_u32 s24, s24, 0x1000
	s_addc_u32 s25, s25, 0
	s_add_u32 s26, s26, 0x1000
	s_addc_u32 s27, s27, 0
.Lsc_pl3:
	s_cmp_gt_u32 s8, 4
	s_cbranch_scc0 .Lsc_pl4
	global_load_dwordx4 v[42:45], v1, s[24:25]
	global_load_dwordx4 v[46:49], v1, s[26:27]
	s_add_u32 s24, s24, 0x1000
	s_addc_u32 s25, s25, 0
	s_add_u32 s26, s26, 0x1000
	s_addc_u32 s27, s27, 0
.Lsc_pl4:
	s_cmp_gt_u32 s8, 5
	s_cbranch_scc0 .Lsc_pl5
	global_load_dwordx4 v[50:53], v1, s[24:25]
	global_load_dwordx4 v[54:57], v1, s[26:27]
	s_add_u32 s24, s24, 0x1000
	s_addc_u32 s25, s25, 0
	s_add_u32 s26, s26, 0x1000
	s_addc_u32 s27, s27, 0
.Lsc_pl5:
	s_cmp_gt_u32 s8, 6
	s_cbranch_scc0 .Lsc_pl6
	global_load_dwordx4 v[58:61], v1, s[24:25]
	global_load_dwordx4 v[62:65], v1, s[26:27]
	s_add_u32 s24, s24, 0x1000
	s_addc_u32 s25, s25, 0
	s_add_u32 s26, s26, 0x1000
	s_addc_u32 s27, s27, 0
.Lsc_pl6:
	s_waitcnt vmcnt(0)
	s_cmp_gt_u32 s8, 0
	s_cbranch_scc0 .Lsc_pf0
	v_fma_f32 v4, v4, v10, v14
	v_fma_f32 v5, v5, v11, v15
	v_fma_f32 v6, v6, v12, v16
	v_fma_f32 v7, v7, v13, v17
.Lsc_pf0:
	s_cmp_gt_u32 s8, 1
	s_cbranch_scc0 .Lsc_pf1
	v_fma_f32 v4, v4, v18, v22
	v_fma_f32 v5, v5, v19, v23
	v_fma_f32 v6, v6, v20, v24
	v_fma_f32 v7, v7, v21, v25
.Lsc_pf1:
	s_cmp_gt_u32 s8, 2
	s_cbranch_scc0 .Lsc_pf2
	v_fma_f32 v4, v4, v26, v30
	v_fma_f32 v5, v5, v27, v31
	v_fma_f32 v6, v6, v28, v32
	v_fma_f32 v7, v7, v29, v33
.Lsc_pf2:
	s_cmp_gt_u32 s8, 3
	s_cbranch_scc0 .Lsc_pf3
	v_fma_f32 v4, v4, v34, v38
	v_fma_f32 v5, v5, v35, v39
	v_fma_f32 v6, v6, v36, v40
	v_fma_f32 v7, v7, v37, v41
.Lsc_pf3:
	s_cmp_gt_u32 s8, 4
	s_cbranch_scc0 .Lsc_pf4
	v_fma_f32 v4, v4, v42, v46
	v_fma_f32 v5, v5, v43, v47
	v_fma_f32 v6, v6, v44, v48
	v_fma_f32 v7, v7, v45, v49
.Lsc_pf4:
	s_cmp_gt_u32 s8, 5
	s_cbranch_scc0 .Lsc_pf5
	v_fma_f32 v4, v4, v50, v54
	v_fma_f32 v5, v5, v51, v55
	v_fma_f32 v6, v6, v52, v56
	v_fma_f32 v7, v7, v53, v57
.Lsc_pf5:
	s_cmp_gt_u32 s8, 6
	s_cbranch_scc0 .Lsc_pf6
	v_fma_f32 v4, v4, v58, v62
	v_fma_f32 v5, v5, v59, v63
	v_fma_f32 v6, v6, v60, v64
	v_fma_f32 v7, v7, v61, v65
.Lsc_pf6:
.Lsc_remdone:
	s_cmp_eq_u32 s9, 0
	s_cbranch_scc1 .Lsc_predone
	global_load_dwordx4 v[10:13], v1, s[24:25]
	global_load_dwordx4 v[14:17], v1, s[26:27]
	s_add_u32 s24, s24, 0x1000
	s_addc_u32 s25, s25, 0
	s_add_u32 s26, s26, 0x1000
	s_addc_u32 s27, s27, 0
	global_load_dwordx4 v[18:21], v1, s[24:25]
	global_load_dwordx4 v[22:25], v1, s[26:27]
	s_add_u32 s24, s24, 0x1000
	s_addc_u32 s25, s25, 0
	s_add_u32 s26, s26, 0x1000
	s_addc_u32 s27, s27, 0
	global_load_dwordx4 v[26:29], v1, s[24:25]
	global_load_dwordx4 v[30:33], v1, s[26:27]
	s_add_u32 s24, s24, 0x1000
	s_addc_u32 s25, s25, 0
	s_add_u32 s26, s26, 0x1000
	s_addc_u32 s27, s27, 0
	global_load_dwordx4 v[34:37], v1, s[24:25]
	global_load_dwordx4 v[38:41], v1, s[26:27]
	s_add_u32 s24, s24, 0x1000
	s_addc_u32 s25, s25, 0
	s_add_u32 s26, s26, 0x1000
	s_addc_u32 s27, s27, 0
	global_load_dwordx4 v[42:45], v1, s[24:25]
	global_load_dwordx4 v[46:49], v1, s[26:27]
	s_add_u32 s24, s24, 0x1000
	s_addc_u32 s25, s25, 0
	s_add_u32 s26, s26, 0x1000
	s_addc_u32 s27, s27, 0
	global_load_dwordx4 v[50:53], v1, s[24:25]
	global_load_dwordx4 v[54:57], v1, s[26:27]
	s_add_u32 s24, s24, 0x1000
	s_addc_u32 s25, s25, 0
	s_add_u32 s26, s26, 0x1000
	s_addc_u32 s27, s27, 0
	global_load_dwordx4 v[58:61], v1, s[24:25]
	global_load_dwordx4 v[62:65], v1, s[26:27]
	s_add_u32 s24, s24, 0x1000
	s_addc_u32 s25, s25, 0
	s_add_u32 s26, s26, 0x1000
	s_addc_u32 s27, s27, 0
	global_load_dwordx4 v[66:69], v1, s[24:25]
	global_load_dwordx4 v[70:73], v1, s[26:27]
	s_add_u32 s24, s24, 0x1000
	s_addc_u32 s25, s25, 0
	s_add_u32 s26, s26, 0x1000
	s_addc_u32 s27, s27, 0
; DEV void ph_scan2(const Params& p, int item) {
;     ...
;   for (int c2 = 0; c2 < c; ++c2) {
;     float4 a = *(const float4*)(p.csA + (size_t)(b * NCH + c2) * 1024 + ch);
;     float4 hh = *(const float4*)(p.csH + (size_t)(b * NCH + c2) * 1024 + ch);
;     H[0] = a.x * H[0] + hh.x; H[1] = a.y * H[1] + hh.y; H[2] = a.z * H[2] + hh.z; H[3] = a.w * H[3] + hh.w;
;   }
.Lsc_full:
	s_sub_u32 s9, s9, 1
	s_cmp_eq_u32 s9, 0
	s_cbranch_scc1 .Lsc_lastA
	global_load_dwordx4 v[80:83], v1, s[24:25]
	global_load_dwordx4 v[84:87], v1, s[26:27]
	s_add_u32 s24, s24, 0x1000
	s_addc_u32 s25, s25, 0
	s_add_u32 s26, s26, 0x1000
	s_addc_u32 s27, s27, 0
	global_load_dwordx4 v[88:91], v1, s[24:25]
	global_load_dwordx4 v[92:95], v1, s[26:27]
	s_add_u32 s24, s24, 0x1000
	s_addc_u32 s25, s25, 0
	s_add_u32 s26, s26, 0x1000
	s_addc_u32 s27, s27, 0
	global_load_dwordx4 v[96:99], v1, s[24:25]
	global_load_dwordx4 v[100:103], v1, s[26:27]
	s_add_u32 s24, s24, 0x1000
	s_addc_u32 s25, s25, 0
	s_add_u32 s26, s26, 0x1000
	s_addc_u32 s27, s27, 0
	global_load_dwordx4 v[104:107], v1, s[24:25]
	global_load_dwordx4 v[108:111], v1, s[26:27]
	s_add_u32 s24, s24, 0x1000
	s_addc_u32 s25, s25, 0
	s_add_u32 s26, s26, 0x1000
	s_addc_u32 s27, s27, 0
	global_load_dwordx4 v[112:115], v1, s[24:25]
	global_load_dwordx4 v[116:119], v1, s[26:27]
	s_add_u32 s24, s24, 0x1000
	s_addc_u32 s25, s25, 0
	s_add_u32 s26, s26, 0x1000
	s_addc_u32 s27, s27, 0
	global_load_dwordx4 v[120:123], v1, s[24:25]
	global_load_dwordx4 v[124:127], v1, s[26:27]
	s_add_u32 s24, s24, 0x1000
	s_addc_u32 s25, s25, 0
	s_add_u32 s26, s26, 0x1000
	s_addc_u32 s27, s27, 0
	global_load_dwordx4 v[128:131], v1, s[24:25]
	global_load_dwordx4 v[132:135], v1, s[26:27]
	s_add_u32 s24, s24, 0x1000
	s_addc_u32 s25, s25, 0
	s_add_u32 s26, s26, 0x1000
	s_addc_u32 s27, s27, 0
	global_load_dwordx4 v[136:139], v1, s[24:25]
	global_load_dwordx4 v[140:143], v1, s[26:27]
	s_add_u32 s24, s24, 0x1000
	s_addc_u32 s25, s25, 0
	s_add_u32 s26, s26, 0x1000
	s_addc_u32 s27, s27, 0
	s_waitcnt vmcnt(16)
	v_fma_f32 v4, v4, v10, v14
	v_fma_f32 v5, v5, v11, v15
	v_fma_f32 v6, v6, v12, v16
	v_fma_f32 v7, v7, v13, v17
	v_fma_f32 v4, v4, v18, v22
	v_fma_f32 v5, v5, v19, v23
	v_fma_f32 v6, v6, v20, v24
	v_fma_f32 v7, v7, v21, v25
	v_fma_f32 v4, v4, v26, v30
	v_fma_f32 v5, v5, v27, v31
	v_fma_f32 v6, v6, v28, v32
	v_fma_f32 v7, v7, v29, v33
	v_fma_f32 v4, v4, v34, v38
	v_fma_f32 v5, v5, v35, v39
	v_fma_f32 v6, v6, v36, v40
	v_fma_f32 v7, v7, v37, v41
	v_fma_f32 v4, v4, v42, v46
	v_fma_f32 v5, v5, v43, v47
	v_fma_f32 v6, v6, v44, v48
	v_fma_f32 v7, v7, v45, v49
	v_fma_f32 v4, v4, v50, v54
	v_fma_f32 v5, v5, v51, v55
	v_fma_f32 v6, v6, v52, v56
	v_fma_f32 v7, v7, v53, v57
	v_fma_f32 v4, v4, v58, v62
	v_fma_f32 v5, v5, v59, v63
	v_fma_f32 v6, v6, v60, v64
	v_fma_f32 v7, v7, v61, v65
	v_fma_f32 v4, v4, v66, v70
	v_fma_f32 v5, v5, v67, v71
	v_fma_f32 v6, v6, v68, v72
	v_fma_f32 v7, v7, v69, v73
	s_sub_u32 s9, s9, 1
	s_cmp_eq_u32 s9, 0
	s_cbranch_scc1 .Lsc_lastB
	global_load_dwordx4 v[10:13], v1, s[24:25]
	global_load_dwordx4 v[14:17], v1, s[26:27]
	s_add_u32 s24, s24, 0x1000
	s_addc_u32 s25, s25, 0
	s_add_u32 s26, s26, 0x1000
	s_addc_u32 s27, s27, 0
	global_load_dwordx4 v[18:21], v1, s[24:25]
	global_load_dwordx4 v[22:25], v1, s[26:27]
	s_add_u32 s24, s24, 0x1000
	s_addc_u32 s25, s25, 0
	s_add_u32 s26, s26, 0x1000
	s_addc_u32 s27, s27, 0
	global_load_dwordx4 v[26:29], v1, s[24:25]
	global_load_dwordx4 v[30:33], v1, s[26:27]
	s_add_u32 s24, s24, 0x1000
	s_addc_u32 s25, s25, 0
	s_add_u32 s26, s26, 0x1000
	s_addc_u32 s27, s27, 0
	global_load_dwordx4 v[34:37], v1, s[24:25]
	global_load_dwordx4 v[38:41], v1, s[26:27]
	s_add_u32 s24, s24, 0x1000
	s_addc_u32 s25, s25, 0
	s_add_u32 s26, s26, 0x1000
	s_addc_u32 s27, s27, 0
	global_load_dwordx4 v[42:45], v1, s[24:25]
	global_load_dwordx4 v[46:49], v1, s[26:27]
	s_add_u32 s24, s24, 0x1000
	s_addc_u32 s25, s25, 0
	s_add_u32 s26, s26, 0x1000
	s_addc_u32 s27, s27, 0
	global_load_dwordx4 v[50:53], v1, s[24:25]
	global_load_dwordx4 v[54:57], v1, s[26:27]
	s_add_u32 s24, s24, 0x1000
	s_addc_u32 s25, s25, 0
	s_add_u32 s26, s26, 0x1000
	s_addc_u32 s27, s27, 0
	global_load_dwordx4 v[58:61], v1, s[24:25]
	global_load_dwordx4 v[62:65], v1, s[26:27]
	s_add_u32 s24, s24, 0x1000
	s_addc_u32 s25, s25, 0
	s_add_u32 s26, s26, 0x1000
	s_addc_u32 s27, s27, 0
	global_load_dwordx4 v[66:69], v1, s[24:25]
	global_load_dwordx4 v[70:73], v1, s[26:27]
	s_add_u32 s24, s24, 0x1000
	s_addc_u32 s25, s25, 0
	s_add_u32 s26, s26, 0x1000
	s_addc_u32 s27, s27, 0
	s_waitcnt vmcnt(16)
	v_fma_f32 v4, v4, v80, v84
	v_fma_f32 v5, v5, v81, v85
	v_fma_f32 v6, v6, v82, v86
	v_fma_f32 v7, v7, v83, v87
	v_fma_f32 v4, v4, v88, v92
	v_fma_f32 v5, v5, v89, v93
	v_fma_f32 v6, v6, v90, v94
	v_fma_f32 v7, v7, v91, v95
	v_fma_f32 v4, v4, v96, v100
	v_fma_f32 v5, v5, v97, v101
	v_fma_f32 v6, v6, v98, v102
	v_fma_f32 v7, v7, v99, v103
	v_fma_f32 v4, v4, v104, v108
	v_fma_f32 v5, v5, v105, v109
	v_fma_f32 v6, v6, v106, v110
	v_fma_f32 v7, v7, v107, v111
	v_fma_f32 v4, v4, v112, v116
	v_fma_f32 v5, v5, v113, v117
	v_fma_f32 v6, v6, v114, v118
	v_fma_f32 v7, v7, v115, v119
	v_fma_f32 v4, v4, v120, v124
	v_fma_f32 v5, v5, v121, v125
	v_fma_f32 v6, v6, v122, v126
	v_fma_f32 v7, v7, v123, v127
	v_fma_f32 v4, v4, v128, v132
	v_fma_f32 v5, v5, v129, v133
	v_fma_f32 v6, v6, v130, v134
	v_fma_f32 v7, v7, v131, v135
	v_fma_f32 v4, v4, v136, v140
	v_fma_f32 v5, v5, v137, v141
	v_fma_f32 v6, v6, v138, v142
	v_fma_f32 v7, v7, v139, v143
	s_branch .Lsc_full
; DEV void ph_scan2(const Params& p, int item) {
;     ...
;   for (int c2 = 0; c2 < c; ++c2) {
;     float4 a = *(const float4*)(p.csA + (size_t)(b * NCH + c2) * 1024 + ch);
;     float4 hh = *(const float4*)(p.csH + (size_t)(b * NCH + c2) * 1024 + ch);
;     H[0] = a.x * H[0] + hh.x; H[1] = a.y * H[1] + hh.y; H[2] = a.z * H[2] + hh.z; H[3] = a.w * H[3] + hh.w;
;   }
.Lsc_lastA:
	s_waitcnt vmcnt(0)
	v_fma_f32 v4, v4, v10, v14
	v_fma_f32 v5, v5, v11, v15
	v_fma_f32 v6, v6, v12, v16
	v_fma_f32 v7, v7, v13, v17
	v_fma_f32 v4, v4, v18, v22
	v_fma_f32 v5, v5, v19, v23
	v_fma_f32 v6, v6, v20, v24
	v_fma_f32 v7, v7, v21, v25
	v_fma_f32 v4, v4, v26, v30
	v_fma_f32 v5, v5, v27, v31
	v_fma_f32 v6, v6, v28, v32
	v_fma_f32 v7, v7, v29, v33
	v_fma_f32 v4, v4, v34, v38
	v_fma_f32 v5, v5, v35, v39
	v_fma_f32 v6, v6, v36, v40
	v_fma_f32 v7, v7, v37, v41
	v_fma_f32 v4, v4, v42, v46
	v_fma_f32 v5, v5, v43, v47
	v_fma_f32 v6, v6, v44, v48
	v_fma_f32 v7, v7, v45, v49
	v_fma_f32 v4, v4, v50, v54
	v_fma_f32 v5, v5, v51, v55
	v_fma_f32 v6, v6, v52, v56
	v_fma_f32 v7, v7, v53, v57
	v_fma_f32 v4, v4, v58, v62
	v_fma_f32 v5, v5, v59, v63
	v_fma_f32 v6, v6, v60, v64
	v_fma_f32 v7, v7, v61, v65
	v_fma_f32 v4, v4, v66, v70
	v_fma_f32 v5, v5, v67, v71
	v_fma_f32 v6, v6, v68, v72
	v_fma_f32 v7, v7, v69, v73
	s_branch .Lsc_predone
.Lsc_lastB:
	s_waitcnt vmcnt(0)
	v_fma_f32 v4, v4, v80, v84
	v_fma_f32 v5, v5, v81, v85
	v_fma_f32 v6, v6, v82, v86
	v_fma_f32 v7, v7, v83, v87
	v_fma_f32 v4, v4, v88, v92
	v_fma_f32 v5, v5, v89, v93
	v_fma_f32 v6, v6, v90, v94
	v_fma_f32 v7, v7, v91, v95
	v_fma_f32 v4, v4, v96, v100
	v_fma_f32 v5, v5, v97, v101
	v_fma_f32 v6, v6, v98, v102
	v_fma_f32 v7, v7, v99, v103
	v_fma_f32 v4, v4, v104, v108
	v_fma_f32 v5, v5, v105, v109
	v_fma_f32 v6, v6, v106, v110
	v_fma_f32 v7, v7, v107, v111
	v_fma_f32 v4, v4, v112, v116
	v_fma_f32 v5, v5, v113, v117
	v_fma_f32 v6, v6, v114, v118
	v_fma_f32 v7, v7, v115, v119
	v_fma_f32 v4, v4, v120, v124
	v_fma_f32 v5, v5, v121, v125
	v_fma_f32 v6, v6, v122, v126
	v_fma_f32 v7, v7, v123, v127
	v_fma_f32 v4, v4, v128, v132
	v_fma_f32 v5, v5, v129, v133
	v_fma_f32 v6, v6, v130, v134
	v_fma_f32 v7, v7, v131, v135
	v_fma_f32 v4, v4, v136, v140
	v_fma_f32 v5, v5, v137, v141
	v_fma_f32 v6, v6, v138, v142
	v_fma_f32 v7, v7, v139, v143
